# fix MFMA->cvt hazard in NSA compression MLP2 (s_nop 11 at 4 sites), no other change
# speedup vs baseline: 1.0022x; 1.0022x over previous
.LBB0_1306:
	s_or_b64 exec, exec, s[6:7]
	s_lshl_b32 s0, s20, 8
	s_ashr_i32 s1, s21, 1
	s_and_b32 s0, s0, 0x700
	s_andn2_b32 s1, s1, 31
	v_and_b32_e32 v15, 31, v17
	s_add_i32 s6, s1, s0
	v_or_b32_e32 v2, s6, v15
	v_ashrrev_i32_e32 v3, 31, v2
	v_bfe_u32 v18, v17, 5, 1
	v_lshlrev_b64 v[2:3], 8, v[2:3]
	v_lshl_add_u64 v[2:3], s[4:5], 0, v[2:3]
	v_lshlrev_b32_e32 v0, 4, v18
	v_lshl_add_u64 v[2:3], v[2:3], 0, v[0:1]
	s_waitcnt lgkmcnt(0)
	s_barrier
	flat_load_dwordx4 v[50:53], v[2:3]
	flat_load_dwordx4 v[46:49], v[2:3] offset:32
	flat_load_dwordx4 v[42:45], v[2:3] offset:64
	flat_load_dwordx4 v[38:41], v[2:3] offset:96
	flat_load_dwordx4 v[34:37], v[2:3] offset:128
	flat_load_dwordx4 v[10:13], v[2:3] offset:160
	flat_load_dwordx4 v[6:9], v[2:3] offset:192
	s_nop 0
	flat_load_dwordx4 v[2:5], v[2:3] offset:224
	s_add_u32 s0, s8, s2
	v_lshl_or_b32 v86, v18, 2, s6
	v_lshlrev_b32_e32 v18, 1, v15
	v_mul_u32_u24_e32 v15, 0x88, v15
	s_addc_u32 s1, s9, s3
	v_mov_b32_e32 v19, v1
	v_lshlrev_b32_e32 v15, 1, v15
	v_lshl_add_u64 v[18:19], s[0:1], 0, v[18:19]
	s_mov_b64 s[0:1], 0x58211000
	v_add3_u32 v0, 0, v0, v15
	v_lshl_add_u64 v[84:85], v[18:19], 0, s[0:1]
	ds_read_b128 v[54:57], v0 offset:34816
	ds_read_b128 v[18:21], v0
	ds_read_b128 v[58:61], v0 offset:32
	v_ashrrev_i32_e32 v87, 31, v86
	s_mov_b64 s[0:1], 0
	s_waitcnt vmcnt(0) lgkmcnt(0)
	v_mfma_f32_32x32x16_bf16 v[18:33], v[50:53], v[18:21], 0
	v_mfma_f32_32x32x16_bf16 v[18:33], v[50:53], v[54:57], v[18:33]
	ds_read_b128 v[54:57], v0 offset:34848
	v_mfma_f32_32x32x16_bf16 v[18:33], v[46:49], v[58:61], v[18:33]
	s_waitcnt lgkmcnt(0)
	v_mfma_f32_32x32x16_bf16 v[18:33], v[46:49], v[54:57], v[18:33]
	ds_read_b128 v[54:57], v0 offset:64
	ds_read_b128 v[58:61], v0 offset:34880
	s_waitcnt lgkmcnt(1)
	v_mfma_f32_32x32x16_bf16 v[18:33], v[42:45], v[54:57], v[18:33]
	s_waitcnt lgkmcnt(0)
	v_mfma_f32_32x32x16_bf16 v[18:33], v[42:45], v[58:61], v[18:33]
	ds_read_b128 v[54:57], v0 offset:96
	ds_read_b128 v[58:61], v0 offset:34912
	s_waitcnt lgkmcnt(1)
	v_mfma_f32_32x32x16_bf16 v[18:33], v[38:41], v[54:57], v[18:33]
	s_waitcnt lgkmcnt(0)
	v_mfma_f32_32x32x16_bf16 v[18:33], v[38:41], v[58:61], v[18:33]
	ds_read_b128 v[54:57], v0 offset:128
	ds_read_b128 v[58:61], v0 offset:34944
	s_waitcnt lgkmcnt(1)
	v_mfma_f32_32x32x16_bf16 v[18:33], v[34:37], v[54:57], v[18:33]
	s_waitcnt lgkmcnt(0)
	v_mfma_f32_32x32x16_bf16 v[18:33], v[34:37], v[58:61], v[18:33]
	ds_read_b128 v[54:57], v0 offset:160
	ds_read_b128 v[58:61], v0 offset:34976
	s_waitcnt lgkmcnt(1)
	v_mfma_f32_32x32x16_bf16 v[18:33], v[10:13], v[54:57], v[18:33]
	s_waitcnt lgkmcnt(0)
	v_mfma_f32_32x32x16_bf16 v[18:33], v[10:13], v[58:61], v[18:33]
	ds_read_b128 v[54:57], v0 offset:192
	ds_read_b128 v[58:61], v0 offset:35008
	s_waitcnt lgkmcnt(1)
	v_mfma_f32_32x32x16_bf16 v[18:33], v[6:9], v[54:57], v[18:33]
	s_waitcnt lgkmcnt(0)
	v_mfma_f32_32x32x16_bf16 v[18:33], v[6:9], v[58:61], v[18:33]
	ds_read_b128 v[54:57], v0 offset:224
	ds_read_b128 v[58:61], v0 offset:35040
	s_waitcnt lgkmcnt(1)
	v_mfma_f32_32x32x16_bf16 v[18:33], v[2:5], v[54:57], v[18:33]
	v_lshlrev_b64 v[54:55], 8, v[86:87]
	v_lshl_add_u64 v[54:55], v[84:85], 0, v[54:55]
	s_waitcnt lgkmcnt(0)
	v_mfma_f32_32x32x16_bf16 v[18:33], v[2:5], v[58:61], v[18:33]
	s_nop 11
	v_cvt_pk_bf16_f32 v15, v18, v1
	flat_store_short v[54:55], v15
	v_cvt_pk_bf16_f32 v15, v19, v1
	s_nop 10
	v_or_b32_e32 v18, 1, v86
	v_ashrrev_i32_e32 v19, 31, v18
	v_lshlrev_b64 v[18:19], 8, v[18:19]
	v_lshl_add_u64 v[56:57], v[84:85], 0, v[18:19]
	v_or_b32_e32 v18, 2, v86
	v_ashrrev_i32_e32 v19, 31, v18
	v_lshlrev_b64 v[18:19], 8, v[18:19]
	v_lshl_add_u64 v[58:59], v[84:85], 0, v[18:19]
	v_or_b32_e32 v18, 3, v86
	v_ashrrev_i32_e32 v19, 31, v18
	v_lshlrev_b64 v[18:19], 8, v[18:19]
	v_lshl_add_u64 v[60:61], v[84:85], 0, v[18:19]
	v_or_b32_e32 v18, 8, v86
	v_ashrrev_i32_e32 v19, 31, v18
	v_lshlrev_b64 v[18:19], 8, v[18:19]
	v_lshl_add_u64 v[62:63], v[84:85], 0, v[18:19]
	v_or_b32_e32 v18, 9, v86
	v_ashrrev_i32_e32 v19, 31, v18
	v_lshlrev_b64 v[18:19], 8, v[18:19]
	v_lshl_add_u64 v[64:65], v[84:85], 0, v[18:19]
	v_or_b32_e32 v18, 10, v86
	v_ashrrev_i32_e32 v19, 31, v18
	v_lshlrev_b64 v[18:19], 8, v[18:19]
	v_lshl_add_u64 v[66:67], v[84:85], 0, v[18:19]
	v_or_b32_e32 v18, 11, v86
	v_ashrrev_i32_e32 v19, 31, v18
	v_lshlrev_b64 v[18:19], 8, v[18:19]
	v_lshl_add_u64 v[68:69], v[84:85], 0, v[18:19]
	v_or_b32_e32 v18, 16, v86
	v_ashrrev_i32_e32 v19, 31, v18
	v_lshlrev_b64 v[18:19], 8, v[18:19]
	v_lshl_add_u64 v[70:71], v[84:85], 0, v[18:19]
	v_or_b32_e32 v18, 17, v86
	v_ashrrev_i32_e32 v19, 31, v18
	v_lshlrev_b64 v[18:19], 8, v[18:19]
	v_lshl_add_u64 v[72:73], v[84:85], 0, v[18:19]
	v_or_b32_e32 v18, 18, v86
	v_ashrrev_i32_e32 v19, 31, v18
	v_lshlrev_b64 v[18:19], 8, v[18:19]
	v_lshl_add_u64 v[74:75], v[84:85], 0, v[18:19]
	v_or_b32_e32 v18, 19, v86
	v_ashrrev_i32_e32 v19, 31, v18
	v_lshlrev_b64 v[18:19], 8, v[18:19]
	flat_store_short v[56:57], v15
	v_cvt_pk_bf16_f32 v15, v20, v1
	v_lshl_add_u64 v[76:77], v[84:85], 0, v[18:19]
	v_or_b32_e32 v18, 24, v86
	flat_store_short v[58:59], v15
	v_cvt_pk_bf16_f32 v15, v21, v1
	v_ashrrev_i32_e32 v19, 31, v18
	flat_store_short v[60:61], v15
	v_cvt_pk_bf16_f32 v15, v22, v1
	v_lshlrev_b64 v[18:19], 8, v[18:19]
	flat_store_short v[62:63], v15
	v_cvt_pk_bf16_f32 v15, v23, v1
	v_lshl_add_u64 v[78:79], v[84:85], 0, v[18:19]
	v_or_b32_e32 v18, 25, v86
	flat_store_short v[64:65], v15
	v_cvt_pk_bf16_f32 v15, v24, v1
	v_ashrrev_i32_e32 v19, 31, v18
	flat_store_short v[66:67], v15
	v_cvt_pk_bf16_f32 v15, v25, v1
	v_lshlrev_b64 v[18:19], 8, v[18:19]
	flat_store_short v[68:69], v15
	v_cvt_pk_bf16_f32 v15, v26, v1
	v_lshl_add_u64 v[80:81], v[84:85], 0, v[18:19]
	v_or_b32_e32 v18, 26, v86
	flat_store_short v[70:71], v15
	v_cvt_pk_bf16_f32 v15, v27, v1
	v_ashrrev_i32_e32 v19, 31, v18
	flat_store_short v[72:73], v15
	v_cvt_pk_bf16_f32 v15, v28, v1
	v_lshlrev_b64 v[18:19], 8, v[18:19]
	flat_store_short v[74:75], v15
	v_cvt_pk_bf16_f32 v15, v29, v1
	v_lshl_add_u64 v[82:83], v[84:85], 0, v[18:19]
	v_or_b32_e32 v18, 27, v86
	flat_store_short v[76:77], v15
	v_cvt_pk_bf16_f32 v15, v30, v1
	v_ashrrev_i32_e32 v19, 31, v18
	flat_store_short v[78:79], v15
	v_cvt_pk_bf16_f32 v15, v31, v1
	v_lshlrev_b64 v[18:19], 8, v[18:19]
	flat_store_short v[80:81], v15
	v_cvt_pk_bf16_f32 v15, v32, v1
	v_lshl_add_u64 v[84:85], v[84:85], 0, v[18:19]
	flat_store_short v[82:83], v15
	v_cvt_pk_bf16_f32 v15, v33, v1
	flat_store_short v[84:85], v15
	ds_read_b128 v[86:89], v0 offset:43520
	ds_read_b128 v[18:21], v0 offset:8704
	ds_read_b128 v[90:93], v0 offset:8736
	s_waitcnt lgkmcnt(0)
	v_mfma_f32_32x32x16_bf16 v[18:33], v[50:53], v[18:21], 0
	v_mfma_f32_32x32x16_bf16 v[18:33], v[50:53], v[86:89], v[18:33]
	ds_read_b128 v[86:89], v0 offset:43552
	v_mfma_f32_32x32x16_bf16 v[18:33], v[46:49], v[90:93], v[18:33]
	s_waitcnt lgkmcnt(0)
	v_mfma_f32_32x32x16_bf16 v[18:33], v[46:49], v[86:89], v[18:33]
	ds_read_b128 v[86:89], v0 offset:8768
	ds_read_b128 v[90:93], v0 offset:43584
	s_waitcnt lgkmcnt(0)
	v_mfma_f32_32x32x16_bf16 v[18:33], v[42:45], v[86:89], v[18:33]
	v_mfma_f32_32x32x16_bf16 v[18:33], v[42:45], v[90:93], v[18:33]
	ds_read_b128 v[86:89], v0 offset:8800
	ds_read_b128 v[90:93], v0 offset:43616
	s_waitcnt lgkmcnt(0)
	v_mfma_f32_32x32x16_bf16 v[18:33], v[38:41], v[86:89], v[18:33]
	v_mfma_f32_32x32x16_bf16 v[18:33], v[38:41], v[90:93], v[18:33]
	ds_read_b128 v[86:89], v0 offset:8832
	ds_read_b128 v[90:93], v0 offset:43648
	s_waitcnt lgkmcnt(0)
	v_mfma_f32_32x32x16_bf16 v[18:33], v[34:37], v[86:89], v[18:33]
	v_mfma_f32_32x32x16_bf16 v[18:33], v[34:37], v[90:93], v[18:33]
	ds_read_b128 v[86:89], v0 offset:8864
	ds_read_b128 v[90:93], v0 offset:43680
	s_waitcnt lgkmcnt(0)
	v_mfma_f32_32x32x16_bf16 v[18:33], v[10:13], v[86:89], v[18:33]
	v_mfma_f32_32x32x16_bf16 v[18:33], v[10:13], v[90:93], v[18:33]
	ds_read_b128 v[86:89], v0 offset:8896
	ds_read_b128 v[90:93], v0 offset:43712
	s_waitcnt lgkmcnt(0)
	v_mfma_f32_32x32x16_bf16 v[18:33], v[6:9], v[86:89], v[18:33]
	v_mfma_f32_32x32x16_bf16 v[18:33], v[6:9], v[90:93], v[18:33]
	ds_read_b128 v[86:89], v0 offset:8928
	ds_read_b128 v[90:93], v0 offset:43744
	s_waitcnt lgkmcnt(0)
	v_mfma_f32_32x32x16_bf16 v[18:33], v[2:5], v[86:89], v[18:33]
	v_mfma_f32_32x32x16_bf16 v[18:33], v[2:5], v[90:93], v[18:33]
	s_nop 11
	v_cvt_pk_bf16_f32 v15, v18, v1
	flat_store_short v[54:55], v15 offset:64
	v_cvt_pk_bf16_f32 v15, v19, v1
	flat_store_short v[56:57], v15 offset:64
	v_cvt_pk_bf16_f32 v15, v20, v1
	flat_store_short v[58:59], v15 offset:64
	v_cvt_pk_bf16_f32 v15, v21, v1
	flat_store_short v[60:61], v15 offset:64
	v_cvt_pk_bf16_f32 v15, v22, v1
	flat_store_short v[62:63], v15 offset:64
	v_cvt_pk_bf16_f32 v15, v23, v1
	flat_store_short v[64:65], v15 offset:64
	v_cvt_pk_bf16_f32 v15, v24, v1
	flat_store_short v[66:67], v15 offset:64
	v_cvt_pk_bf16_f32 v15, v25, v1
	flat_store_short v[68:69], v15 offset:64
	v_cvt_pk_bf16_f32 v15, v26, v1
	flat_store_short v[70:71], v15 offset:64
	v_cvt_pk_bf16_f32 v15, v27, v1
	flat_store_short v[72:73], v15 offset:64
	v_cvt_pk_bf16_f32 v15, v28, v1
	flat_store_short v[74:75], v15 offset:64
	v_cvt_pk_bf16_f32 v15, v29, v1
	flat_store_short v[76:77], v15 offset:64
	v_cvt_pk_bf16_f32 v15, v30, v1
	flat_store_short v[78:79], v15 offset:64
	v_cvt_pk_bf16_f32 v15, v31, v1
	flat_store_short v[80:81], v15 offset:64
	v_cvt_pk_bf16_f32 v15, v32, v1
	flat_store_short v[82:83], v15 offset:64
	v_cvt_pk_bf16_f32 v15, v33, v1
	flat_store_short v[84:85], v15 offset:64
	ds_read_b128 v[86:89], v0 offset:52224
	ds_read_b128 v[18:21], v0 offset:17408
	ds_read_b128 v[90:93], v0 offset:17440
	s_waitcnt lgkmcnt(0)
	v_mfma_f32_32x32x16_bf16 v[18:33], v[50:53], v[18:21], 0
	v_mfma_f32_32x32x16_bf16 v[18:33], v[50:53], v[86:89], v[18:33]
	ds_read_b128 v[86:89], v0 offset:52256
	v_mfma_f32_32x32x16_bf16 v[18:33], v[46:49], v[90:93], v[18:33]
	s_waitcnt lgkmcnt(0)
	v_mfma_f32_32x32x16_bf16 v[18:33], v[46:49], v[86:89], v[18:33]
	ds_read_b128 v[86:89], v0 offset:17472
	ds_read_b128 v[90:93], v0 offset:52288
	s_waitcnt lgkmcnt(0)
	v_mfma_f32_32x32x16_bf16 v[18:33], v[42:45], v[86:89], v[18:33]
	v_mfma_f32_32x32x16_bf16 v[18:33], v[42:45], v[90:93], v[18:33]
	ds_read_b128 v[86:89], v0 offset:17504
	ds_read_b128 v[90:93], v0 offset:52320
	s_waitcnt lgkmcnt(0)
	v_mfma_f32_32x32x16_bf16 v[18:33], v[38:41], v[86:89], v[18:33]
	v_mfma_f32_32x32x16_bf16 v[18:33], v[38:41], v[90:93], v[18:33]
	ds_read_b128 v[86:89], v0 offset:17536
	ds_read_b128 v[90:93], v0 offset:52352
	s_waitcnt lgkmcnt(0)
	v_mfma_f32_32x32x16_bf16 v[18:33], v[34:37], v[86:89], v[18:33]
	v_mfma_f32_32x32x16_bf16 v[18:33], v[34:37], v[90:93], v[18:33]
	ds_read_b128 v[86:89], v0 offset:17568
	ds_read_b128 v[90:93], v0 offset:52384
	s_waitcnt lgkmcnt(0)
	v_mfma_f32_32x32x16_bf16 v[18:33], v[10:13], v[86:89], v[18:33]
	v_mfma_f32_32x32x16_bf16 v[18:33], v[10:13], v[90:93], v[18:33]
	ds_read_b128 v[86:89], v0 offset:17600
	ds_read_b128 v[90:93], v0 offset:52416
	s_waitcnt lgkmcnt(0)
	v_mfma_f32_32x32x16_bf16 v[18:33], v[6:9], v[86:89], v[18:33]
	v_mfma_f32_32x32x16_bf16 v[18:33], v[6:9], v[90:93], v[18:33]
	ds_read_b128 v[86:89], v0 offset:17632
	ds_read_b128 v[90:93], v0 offset:52448
	s_waitcnt lgkmcnt(0)
	v_mfma_f32_32x32x16_bf16 v[18:33], v[2:5], v[86:89], v[18:33]
	v_mfma_f32_32x32x16_bf16 v[18:33], v[2:5], v[90:93], v[18:33]
	s_nop 11
	v_cvt_pk_bf16_f32 v15, v18, v1
	flat_store_short v[54:55], v15 offset:128
	v_cvt_pk_bf16_f32 v15, v19, v1
	flat_store_short v[56:57], v15 offset:128
	v_cvt_pk_bf16_f32 v15, v20, v1
	flat_store_short v[58:59], v15 offset:128
	v_cvt_pk_bf16_f32 v15, v21, v1
	flat_store_short v[60:61], v15 offset:128
	v_cvt_pk_bf16_f32 v15, v22, v1
	flat_store_short v[62:63], v15 offset:128
	v_cvt_pk_bf16_f32 v15, v23, v1
	flat_store_short v[64:65], v15 offset:128
	v_cvt_pk_bf16_f32 v15, v24, v1
	flat_store_short v[66:67], v15 offset:128
	v_cvt_pk_bf16_f32 v15, v25, v1
	flat_store_short v[68:69], v15 offset:128
	v_cvt_pk_bf16_f32 v15, v26, v1
	flat_store_short v[70:71], v15 offset:128
	v_cvt_pk_bf16_f32 v15, v27, v1
	flat_store_short v[72:73], v15 offset:128
	v_cvt_pk_bf16_f32 v15, v28, v1
	flat_store_short v[74:75], v15 offset:128
	v_cvt_pk_bf16_f32 v15, v29, v1
	flat_store_short v[76:77], v15 offset:128
	v_cvt_pk_bf16_f32 v15, v30, v1
	flat_store_short v[78:79], v15 offset:128
	v_cvt_pk_bf16_f32 v15, v31, v1
	flat_store_short v[80:81], v15 offset:128
	v_cvt_pk_bf16_f32 v15, v32, v1
	flat_store_short v[82:83], v15 offset:128
	v_cvt_pk_bf16_f32 v15, v33, v1
	flat_store_short v[84:85], v15 offset:128
	ds_read_b128 v[86:89], v0 offset:60928
	ds_read_b128 v[18:21], v0 offset:26112
	ds_read_b128 v[90:93], v0 offset:26144
	s_waitcnt lgkmcnt(0)
	v_mfma_f32_32x32x16_bf16 v[18:33], v[50:53], v[18:21], 0
	v_mfma_f32_32x32x16_bf16 v[18:33], v[50:53], v[86:89], v[18:33]
	ds_read_b128 v[50:53], v0 offset:60960
	v_mfma_f32_32x32x16_bf16 v[18:33], v[46:49], v[90:93], v[18:33]
	s_waitcnt lgkmcnt(0)
	v_mfma_f32_32x32x16_bf16 v[18:33], v[46:49], v[50:53], v[18:33]
	ds_read_b128 v[46:49], v0 offset:26176
	ds_read_b128 v[50:53], v0 offset:60992
	s_waitcnt lgkmcnt(0)
	v_mfma_f32_32x32x16_bf16 v[18:33], v[42:45], v[46:49], v[18:33]
	v_mfma_f32_32x32x16_bf16 v[18:33], v[42:45], v[50:53], v[18:33]
	ds_read_b128 v[42:45], v0 offset:26208
	ds_read_b128 v[46:49], v0 offset:61024
	s_waitcnt lgkmcnt(0)
	v_mfma_f32_32x32x16_bf16 v[18:33], v[38:41], v[42:45], v[18:33]
	v_mfma_f32_32x32x16_bf16 v[18:33], v[38:41], v[46:49], v[18:33]
	ds_read_b128 v[38:41], v0 offset:26240
	ds_read_b128 v[42:45], v0 offset:61056
	s_waitcnt lgkmcnt(0)
	v_mfma_f32_32x32x16_bf16 v[18:33], v[34:37], v[38:41], v[18:33]
	v_mfma_f32_32x32x16_bf16 v[18:33], v[34:37], v[42:45], v[18:33]
	ds_read_b128 v[34:37], v0 offset:26272
	ds_read_b128 v[38:41], v0 offset:61088
	s_waitcnt lgkmcnt(0)
	v_mfma_f32_32x32x16_bf16 v[18:33], v[10:13], v[34:37], v[18:33]
	v_mfma_f32_32x32x16_bf16 v[18:33], v[10:13], v[38:41], v[18:33]
	ds_read_b128 v[10:13], v0 offset:26304
	ds_read_b128 v[34:37], v0 offset:61120
	s_waitcnt lgkmcnt(0)
	v_mfma_f32_32x32x16_bf16 v[18:33], v[6:9], v[10:13], v[18:33]
	v_mfma_f32_32x32x16_bf16 v[18:33], v[6:9], v[34:37], v[18:33]
	ds_read_b128 v[6:9], v0 offset:26336
	ds_read_b128 v[10:13], v0 offset:61152
	s_waitcnt lgkmcnt(0)
	v_mfma_f32_32x32x16_bf16 v[18:33], v[2:5], v[6:9], v[18:33]
	v_mfma_f32_32x32x16_bf16 v[18:33], v[2:5], v[10:13], v[18:33]
	s_nop 11
	v_cvt_pk_bf16_f32 v0, v18, v1
	flat_store_short v[54:55], v0 offset:192
	v_cvt_pk_bf16_f32 v0, v19, v1
	flat_store_short v[56:57], v0 offset:192
	v_cvt_pk_bf16_f32 v0, v20, v1
	flat_store_short v[58:59], v0 offset:192
	v_cvt_pk_bf16_f32 v0, v21, v1
	flat_store_short v[60:61], v0 offset:192
	v_cvt_pk_bf16_f32 v0, v22, v1
	flat_store_short v[62:63], v0 offset:192
	v_cvt_pk_bf16_f32 v0, v23, v1
	flat_store_short v[64:65], v0 offset:192
	v_cvt_pk_bf16_f32 v0, v24, v1
	flat_store_short v[66:67], v0 offset:192
	v_cvt_pk_bf16_f32 v0, v25, v1
	flat_store_short v[68:69], v0 offset:192
	v_cvt_pk_bf16_f32 v0, v26, v1
	flat_store_short v[70:71], v0 offset:192
	v_cvt_pk_bf16_f32 v0, v27, v1
	flat_store_short v[72:73], v0 offset:192
	v_cvt_pk_bf16_f32 v0, v28, v1
	flat_store_short v[74:75], v0 offset:192
	v_cvt_pk_bf16_f32 v0, v29, v1
	flat_store_short v[76:77], v0 offset:192
	v_cvt_pk_bf16_f32 v0, v30, v1
	flat_store_short v[78:79], v0 offset:192
	v_cvt_pk_bf16_f32 v0, v31, v1
	flat_store_short v[80:81], v0 offset:192
	v_cvt_pk_bf16_f32 v0, v32, v1
	flat_store_short v[82:83], v0 offset:192
	v_cvt_pk_bf16_f32 v0, v33, v1
	flat_store_short v[84:85], v0 offset:192
	s_waitcnt lgkmcnt(0)
	s_barrier
